# MLP1 (phase 7) epilogue: 24 of 32 bf16 stores per tile widened to 12 dwordx4 via v_permlane16_swap; plus compress fence relax and in-register top-k
# speedup vs baseline: 1.0285x; 1.0115x over previous
; DEVI void phase7(const Params& p, int l, char* lds) {
;     ...
;     float rs8[8];
; #pragma unroll
;     for (int mi = 0; mi < 8; ++mi) rs8[mi] = rsS[wm * 128 + mi * 16 + fr];
; #pragma unroll
;     for (int ni = 0; ni < 4; ++ni)
; #pragma unroll
;       for (int mi = 0; mi < 8; ++mi) {
;         f32x4 v = acc[ni][mi];
; #pragma unroll
;         for (int j = 0; j < 4; ++j) { float r = fmaxf(v[j] * rs8[mi], 0.f); v[j] = r * r; }
;         int n = n0 + wn * 64 + ni * 16 + fq * 4;
;         int m = m0 + wm * 128 + mi * 16 + fr;
;         store_bf4(hid + (long)m * LDH + n, v);
;       }
.LBB0_204:
	v_lshlrev_b32_e32 v0, 2, v179
	v_add3_u32 v0, s44, v181, v0
	ds_read2_b32 v[120:121], v0 offset1:16
	ds_read2_b32 v[118:119], v0 offset0:32 offset1:48
	ds_read2_b32 v[116:117], v0 offset0:64 offset1:80
	ds_read2_b32 v[114:115], v0 offset0:96 offset1:112
	v_or_b32_e32 v122, s45, v183
	v_ashrrev_i32_e32 v123, 31, v122
	v_lshl_add_u64 v[134:135], v[122:123], 1, s[6:7]
	s_waitcnt lgkmcnt(0)
	v_mul_f32_e32 v122, v162, v120
	v_mul_f32_e32 v123, v163, v120
	v_max_f32_e32 v122, 0, v122
	v_max_f32_e32 v123, 0, v123
	v_pk_mul_f32 v[124:125], v[122:123], v[122:123]
	v_mul_f32_e32 v122, v164, v120
	v_mul_f32_e32 v123, v165, v120
	v_max_f32_e32 v122, 0, v122
	v_max_f32_e32 v123, 0, v123
	v_add_u32_e32 v0, s28, v184
	v_pk_mul_f32 v[126:127], v[122:123], v[122:123]
	s_movk_i32 s20, 0x2080
	v_mad_i64_i32 v[122:123], s[4:5], v0, s20, v[134:135]
	v_cvt_pk_bf16_f32 v124, v124, v125
	v_cvt_pk_bf16_f32 v125, v126, v127
	global_store_dwordx2 v[122:123], v[124:125], off
	v_mul_f32_e32 v124, v158, v121
	v_mul_f32_e32 v125, v159, v121
	v_max_f32_e32 v124, 0, v124
	v_max_f32_e32 v125, 0, v125
	v_pk_mul_f32 v[126:127], v[124:125], v[124:125]
	v_mul_f32_e32 v124, v160, v121
	v_mul_f32_e32 v125, v161, v121
	v_max_f32_e32 v124, 0, v124
	v_max_f32_e32 v125, 0, v125
	v_pk_mul_f32 v[128:129], v[124:125], v[124:125]
	v_or_b32_e32 v124, 16, v0
	v_mad_i64_i32 v[124:125], s[4:5], v124, s20, v[134:135]
	v_cvt_pk_bf16_f32 v126, v126, v127
	v_cvt_pk_bf16_f32 v127, v128, v129
	global_store_dwordx2 v[124:125], v[126:127], off
	v_mul_f32_e32 v126, v150, v118
	v_mul_f32_e32 v127, v151, v118
	v_max_f32_e32 v126, 0, v126
	v_max_f32_e32 v127, 0, v127
	v_pk_mul_f32 v[128:129], v[126:127], v[126:127]
	v_mul_f32_e32 v126, v152, v118
	v_mul_f32_e32 v127, v153, v118
	v_max_f32_e32 v126, 0, v126
	v_max_f32_e32 v127, 0, v127
	v_pk_mul_f32 v[136:137], v[126:127], v[126:127]
	v_or_b32_e32 v126, 32, v0
	v_mad_i64_i32 v[126:127], s[4:5], v126, s20, v[134:135]
	v_cvt_pk_bf16_f32 v128, v128, v129
	v_cvt_pk_bf16_f32 v129, v136, v137
	global_store_dwordx2 v[126:127], v[128:129], off
	v_mul_f32_e32 v128, v130, v119
	v_mul_f32_e32 v129, v131, v119
	v_max_f32_e32 v128, 0, v128
	v_max_f32_e32 v129, 0, v129
	v_pk_mul_f32 v[130:131], v[128:129], v[128:129]
	v_mul_f32_e32 v128, v132, v119
	v_mul_f32_e32 v129, v133, v119
	v_max_f32_e32 v128, 0, v128
	v_max_f32_e32 v129, 0, v129
	v_pk_mul_f32 v[132:133], v[128:129], v[128:129]
	v_or_b32_e32 v128, 48, v0
	v_mul_f32_e32 v110, v110, v116
	v_mul_f32_e32 v111, v111, v116
	v_mad_i64_i32 v[128:129], s[4:5], v128, s20, v[134:135]
	v_cvt_pk_bf16_f32 v130, v130, v131
	v_cvt_pk_bf16_f32 v131, v132, v133
	v_max_f32_e32 v110, 0, v110
	v_max_f32_e32 v111, 0, v111
	global_store_dwordx2 v[128:129], v[130:131], off
	v_pk_mul_f32 v[130:131], v[110:111], v[110:111]
	v_mul_f32_e32 v110, v112, v116
	v_mul_f32_e32 v111, v113, v116
	v_max_f32_e32 v110, 0, v110
	v_max_f32_e32 v111, 0, v111
	v_mul_f32_e32 v106, v106, v117
	v_mul_f32_e32 v107, v107, v117
	v_pk_mul_f32 v[112:113], v[110:111], v[110:111]
	v_max_f32_e32 v106, 0, v106
	v_max_f32_e32 v107, 0, v107
	v_cvt_pk_bf16_f32 v130, v130, v131
	v_cvt_pk_bf16_f32 v131, v112, v113
	v_pk_mul_f32 v[112:113], v[106:107], v[106:107]
	v_mul_f32_e32 v106, v108, v117
	v_mul_f32_e32 v107, v109, v117
	v_max_f32_e32 v106, 0, v106
	v_max_f32_e32 v107, 0, v107
	v_mul_f32_e32 v102, v102, v114
	v_mul_f32_e32 v103, v103, v114
	v_pk_mul_f32 v[108:109], v[106:107], v[106:107]
	v_max_f32_e32 v102, 0, v102
	v_max_f32_e32 v103, 0, v103
	v_cvt_pk_bf16_f32 v112, v112, v113
	v_cvt_pk_bf16_f32 v113, v108, v109
	v_pk_mul_f32 v[108:109], v[102:103], v[102:103]
	v_mul_f32_e32 v102, v104, v114
	v_mul_f32_e32 v103, v105, v114
	v_max_f32_e32 v102, 0, v102
	v_max_f32_e32 v103, 0, v103
	v_mul_f32_e32 v98, v98, v115
	v_mul_f32_e32 v99, v99, v115
	v_pk_mul_f32 v[104:105], v[102:103], v[102:103]
	v_max_f32_e32 v98, 0, v98
	v_max_f32_e32 v99, 0, v99
	v_cvt_pk_bf16_f32 v108, v108, v109
	v_cvt_pk_bf16_f32 v109, v104, v105
	v_pk_mul_f32 v[104:105], v[98:99], v[98:99]
	v_mul_f32_e32 v98, v100, v115
	v_mul_f32_e32 v99, v101, v115
	v_or_b32_e32 v110, 64, v0
	v_or_b32_e32 v106, 0x50, v0
	v_or_b32_e32 v102, 0x60, v0
	v_max_f32_e32 v98, 0, v98
	v_max_f32_e32 v99, 0, v99
	v_or_b32_e32 v0, 0x70, v0
	v_pk_mul_f32 v[100:101], v[98:99], v[98:99]
	v_mad_i64_i32 v[98:99], s[4:5], v0, s20, v[134:135]
	v_mul_f32_e32 v0, v94, v120
	v_max_f32_e32 v94, 0, v0
	v_mul_f32_e32 v0, v95, v120
	v_max_f32_e32 v95, 0, v0
	v_mul_f32_e32 v0, v96, v120
	v_max_f32_e32 v96, 0, v0
	v_mul_f32_e32 v0, v97, v120
	v_max_f32_e32 v97, 0, v0
	v_mul_f32_e32 v0, v90, v121
	v_max_f32_e32 v90, 0, v0
	v_mul_f32_e32 v0, v91, v121
	v_max_f32_e32 v91, 0, v0
	v_mul_f32_e32 v0, v92, v121
	v_max_f32_e32 v92, 0, v0
	v_mul_f32_e32 v0, v93, v121
	v_max_f32_e32 v93, 0, v0
	v_mul_f32_e32 v0, v86, v118
	v_max_f32_e32 v86, 0, v0
	v_mul_f32_e32 v0, v87, v118
	v_max_f32_e32 v87, 0, v0
	v_mul_f32_e32 v0, v88, v118
	v_max_f32_e32 v88, 0, v0
	v_mul_f32_e32 v0, v89, v118
	v_max_f32_e32 v89, 0, v0
	v_mul_f32_e32 v0, v82, v119
	v_max_f32_e32 v82, 0, v0
	v_mul_f32_e32 v0, v83, v119
	v_max_f32_e32 v83, 0, v0
	v_mul_f32_e32 v0, v84, v119
	v_max_f32_e32 v84, 0, v0
	v_mul_f32_e32 v0, v85, v119
	v_max_f32_e32 v85, 0, v0
	v_mul_f32_e32 v0, v78, v116
	v_max_f32_e32 v78, 0, v0
	v_mul_f32_e32 v0, v79, v116
	v_max_f32_e32 v79, 0, v0
	v_mul_f32_e32 v0, v80, v116
	v_max_f32_e32 v80, 0, v0
	v_mul_f32_e32 v0, v81, v116
	v_max_f32_e32 v81, 0, v0
	v_mul_f32_e32 v0, v74, v117
	v_max_f32_e32 v74, 0, v0
	v_mul_f32_e32 v0, v75, v117
	v_max_f32_e32 v75, 0, v0
	v_mul_f32_e32 v0, v76, v117
	v_max_f32_e32 v76, 0, v0
	v_mul_f32_e32 v0, v77, v117
; DEVI void phase7(const Params& p, int l, char* lds) {
;     ...
;     float rs8[8];
; #pragma unroll
;     for (int mi = 0; mi < 8; ++mi) rs8[mi] = rsS[wm * 128 + mi * 16 + fr];
; #pragma unroll
;     for (int ni = 0; ni < 4; ++ni)
; #pragma unroll
;       for (int mi = 0; mi < 8; ++mi) {
;         f32x4 v = acc[ni][mi];
; #pragma unroll
;         for (int j = 0; j < 4; ++j) { float r = fmaxf(v[j] * rs8[mi], 0.f); v[j] = r * r; }
	v_max_f32_e32 v77, 0, v0
	v_mul_f32_e32 v0, v70, v114
	v_max_f32_e32 v70, 0, v0
	v_mul_f32_e32 v0, v71, v114
	v_max_f32_e32 v71, 0, v0
	v_mul_f32_e32 v0, v72, v114
	v_max_f32_e32 v72, 0, v0
	v_mul_f32_e32 v0, v73, v114
	v_max_f32_e32 v73, 0, v0
	v_mul_f32_e32 v0, v66, v115
	v_max_f32_e32 v66, 0, v0
	v_mul_f32_e32 v0, v67, v115
	v_max_f32_e32 v67, 0, v0
	v_mul_f32_e32 v0, v68, v115
	v_max_f32_e32 v68, 0, v0
	v_mul_f32_e32 v0, v69, v115
	v_max_f32_e32 v69, 0, v0
	v_mul_f32_e32 v0, v62, v120
	v_max_f32_e32 v62, 0, v0
	v_mul_f32_e32 v0, v63, v120
	v_max_f32_e32 v63, 0, v0
	v_mul_f32_e32 v0, v64, v120
	v_max_f32_e32 v64, 0, v0
	v_mul_f32_e32 v0, v65, v120
	v_max_f32_e32 v65, 0, v0
	v_mul_f32_e32 v0, v58, v121
	v_max_f32_e32 v58, 0, v0
	v_mul_f32_e32 v0, v59, v121
	v_max_f32_e32 v59, 0, v0
	v_mul_f32_e32 v0, v60, v121
	v_max_f32_e32 v60, 0, v0
	v_mul_f32_e32 v0, v61, v121
	v_max_f32_e32 v61, 0, v0
	v_mul_f32_e32 v0, v54, v118
	v_max_f32_e32 v54, 0, v0
	v_mul_f32_e32 v0, v55, v118
	v_max_f32_e32 v55, 0, v0
	v_mul_f32_e32 v0, v56, v118
	v_max_f32_e32 v56, 0, v0
	v_mul_f32_e32 v0, v57, v118
	v_max_f32_e32 v57, 0, v0
	v_mul_f32_e32 v0, v50, v119
	v_max_f32_e32 v50, 0, v0
	v_mul_f32_e32 v0, v51, v119
	v_max_f32_e32 v51, 0, v0
	v_mul_f32_e32 v0, v52, v119
	v_max_f32_e32 v52, 0, v0
	v_mul_f32_e32 v0, v53, v119
	v_max_f32_e32 v53, 0, v0
	v_mul_f32_e32 v0, v46, v116
	v_max_f32_e32 v46, 0, v0
	v_mul_f32_e32 v0, v47, v116
	v_max_f32_e32 v47, 0, v0
	v_mul_f32_e32 v0, v48, v116
	v_max_f32_e32 v48, 0, v0
	v_mul_f32_e32 v0, v49, v116
	v_max_f32_e32 v49, 0, v0
	v_mul_f32_e32 v0, v42, v117
	v_max_f32_e32 v42, 0, v0
	v_mul_f32_e32 v0, v43, v117
	v_max_f32_e32 v43, 0, v0
	v_mul_f32_e32 v0, v44, v117
	v_max_f32_e32 v44, 0, v0
	v_mul_f32_e32 v0, v45, v117
	v_max_f32_e32 v45, 0, v0
	v_mul_f32_e32 v0, v38, v114
	v_max_f32_e32 v38, 0, v0
	v_mul_f32_e32 v0, v39, v114
	v_max_f32_e32 v39, 0, v0
	v_mul_f32_e32 v0, v40, v114
	v_max_f32_e32 v40, 0, v0
	v_mul_f32_e32 v0, v41, v114
	v_max_f32_e32 v41, 0, v0
	v_mul_f32_e32 v0, v34, v115
	v_max_f32_e32 v34, 0, v0
	v_mul_f32_e32 v0, v35, v115
	v_max_f32_e32 v35, 0, v0
	v_mul_f32_e32 v0, v36, v115
	v_max_f32_e32 v36, 0, v0
	v_mul_f32_e32 v0, v37, v115
	v_max_f32_e32 v37, 0, v0
	v_mul_f32_e32 v0, v30, v120
	v_max_f32_e32 v30, 0, v0
	v_mul_f32_e32 v0, v31, v120
	v_max_f32_e32 v31, 0, v0
	v_mul_f32_e32 v0, v32, v120
	v_max_f32_e32 v32, 0, v0
	v_mul_f32_e32 v0, v33, v120
	v_max_f32_e32 v33, 0, v0
	v_mul_f32_e32 v0, v26, v121
	v_max_f32_e32 v26, 0, v0
	v_mul_f32_e32 v0, v27, v121
	v_max_f32_e32 v27, 0, v0
	v_mul_f32_e32 v0, v28, v121
	v_max_f32_e32 v28, 0, v0
	v_mul_f32_e32 v0, v29, v121
	v_max_f32_e32 v29, 0, v0
	v_mul_f32_e32 v0, v22, v118
	v_max_f32_e32 v22, 0, v0
	v_mul_f32_e32 v0, v23, v118
	v_max_f32_e32 v23, 0, v0
	v_mul_f32_e32 v0, v24, v118
	v_max_f32_e32 v24, 0, v0
	v_mul_f32_e32 v0, v25, v118
	v_max_f32_e32 v25, 0, v0
	v_mul_f32_e32 v0, v18, v119
	v_max_f32_e32 v18, 0, v0
	v_mul_f32_e32 v0, v19, v119
	v_max_f32_e32 v19, 0, v0
	v_mul_f32_e32 v0, v20, v119
	v_max_f32_e32 v20, 0, v0
	v_mul_f32_e32 v0, v21, v119
	v_max_f32_e32 v21, 0, v0
	v_mul_f32_e32 v0, v14, v116
	v_max_f32_e32 v14, 0, v0
	v_mul_f32_e32 v0, v15, v116
	v_max_f32_e32 v15, 0, v0
	v_mul_f32_e32 v0, v16, v116
	v_max_f32_e32 v16, 0, v0
	v_mul_f32_e32 v0, v17, v116
	v_max_f32_e32 v17, 0, v0
	v_mul_f32_e32 v0, v10, v117
	v_max_f32_e32 v10, 0, v0
	v_mul_f32_e32 v0, v11, v117
	v_max_f32_e32 v11, 0, v0
	v_mul_f32_e32 v0, v12, v117
	v_max_f32_e32 v12, 0, v0
	v_mul_f32_e32 v0, v13, v117
	v_max_f32_e32 v13, 0, v0
	v_mul_f32_e32 v0, v6, v114
	v_max_f32_e32 v6, 0, v0
	v_mul_f32_e32 v0, v7, v114
	v_max_f32_e32 v7, 0, v0
	v_mul_f32_e32 v0, v8, v114
	v_max_f32_e32 v8, 0, v0
	v_mul_f32_e32 v0, v9, v114
	v_max_f32_e32 v9, 0, v0
	v_mul_f32_e32 v0, v2, v115
	v_max_f32_e32 v2, 0, v0
	v_mul_f32_e32 v0, v3, v115
	v_max_f32_e32 v3, 0, v0
	v_mul_f32_e32 v0, v4, v115
	v_max_f32_e32 v4, 0, v0
	v_mul_f32_e32 v0, v5, v115
	v_max_f32_e32 v5, 0, v0
	v_pk_mul_f32 v[94:95], v[94:95], v[94:95]
	v_pk_mul_f32 v[96:97], v[96:97], v[96:97]
	v_pk_mul_f32 v[90:91], v[90:91], v[90:91]
	v_pk_mul_f32 v[92:93], v[92:93], v[92:93]
	v_pk_mul_f32 v[86:87], v[86:87], v[86:87]
	v_pk_mul_f32 v[88:89], v[88:89], v[88:89]
	v_pk_mul_f32 v[82:83], v[82:83], v[82:83]
	v_pk_mul_f32 v[84:85], v[84:85], v[84:85]
	v_pk_mul_f32 v[78:79], v[78:79], v[78:79]
	v_pk_mul_f32 v[80:81], v[80:81], v[80:81]
	v_pk_mul_f32 v[74:75], v[74:75], v[74:75]
	v_pk_mul_f32 v[76:77], v[76:77], v[76:77]
	v_pk_mul_f32 v[70:71], v[70:71], v[70:71]
	v_pk_mul_f32 v[72:73], v[72:73], v[72:73]
	v_pk_mul_f32 v[66:67], v[66:67], v[66:67]
	v_pk_mul_f32 v[68:69], v[68:69], v[68:69]
	v_pk_mul_f32 v[62:63], v[62:63], v[62:63]
	v_pk_mul_f32 v[64:65], v[64:65], v[64:65]
	v_pk_mul_f32 v[58:59], v[58:59], v[58:59]
	v_pk_mul_f32 v[60:61], v[60:61], v[60:61]
	v_pk_mul_f32 v[54:55], v[54:55], v[54:55]
	v_pk_mul_f32 v[56:57], v[56:57], v[56:57]
	v_pk_mul_f32 v[50:51], v[50:51], v[50:51]
	v_pk_mul_f32 v[52:53], v[52:53], v[52:53]
	v_pk_mul_f32 v[46:47], v[46:47], v[46:47]
	v_pk_mul_f32 v[48:49], v[48:49], v[48:49]
	v_pk_mul_f32 v[42:43], v[42:43], v[42:43]
	v_pk_mul_f32 v[44:45], v[44:45], v[44:45]
	v_pk_mul_f32 v[38:39], v[38:39], v[38:39]
	v_pk_mul_f32 v[40:41], v[40:41], v[40:41]
	v_pk_mul_f32 v[34:35], v[34:35], v[34:35]
	v_pk_mul_f32 v[36:37], v[36:37], v[36:37]
	v_pk_mul_f32 v[30:31], v[30:31], v[30:31]
	v_pk_mul_f32 v[32:33], v[32:33], v[32:33]
	v_pk_mul_f32 v[26:27], v[26:27], v[26:27]
	v_pk_mul_f32 v[28:29], v[28:29], v[28:29]
; DEVI void store_bf4(bfu* p, f32x4 v) {
;   uint2 u; u.x = pack2(v[0], v[1]); u.y = pack2(v[2], v[3]);
;   *(uint2*)p = u;
; }
; DEVI void phase7(const Params& p, int l, char* lds) {
;     ...
; #pragma unroll
;     for (int ni = 0; ni < 4; ++ni)
; #pragma unroll
;       for (int mi = 0; mi < 8; ++mi) {
;         f32x4 v = acc[ni][mi];
; #pragma unroll
;         for (int j = 0; j < 4; ++j) { float r = fmaxf(v[j] * rs8[mi], 0.f); v[j] = r * r; }
;         int n = n0 + wn * 64 + ni * 16 + fq * 4;
;         int m = m0 + wm * 128 + mi * 16 + fr;
;         store_bf4(hid + (long)m * LDH + n, v);
;       }
	v_pk_mul_f32 v[22:23], v[22:23], v[22:23]
	v_pk_mul_f32 v[24:25], v[24:25], v[24:25]
	v_pk_mul_f32 v[18:19], v[18:19], v[18:19]
	v_pk_mul_f32 v[20:21], v[20:21], v[20:21]
	v_pk_mul_f32 v[14:15], v[14:15], v[14:15]
	v_pk_mul_f32 v[16:17], v[16:17], v[16:17]
	v_pk_mul_f32 v[10:11], v[10:11], v[10:11]
	v_pk_mul_f32 v[12:13], v[12:13], v[12:13]
	v_pk_mul_f32 v[6:7], v[6:7], v[6:7]
	v_pk_mul_f32 v[8:9], v[8:9], v[8:9]
	v_pk_mul_f32 v[2:3], v[2:3], v[2:3]
	v_pk_mul_f32 v[4:5], v[4:5], v[4:5]
	v_mad_i64_i32 v[110:111], s[4:5], v110, s20, v[134:135]
	v_mad_i64_i32 v[106:107], s[4:5], v106, s20, v[134:135]
	v_mad_i64_i32 v[102:103], s[4:5], v102, s20, v[134:135]
	v_cvt_pk_bf16_f32 v104, v104, v105
	v_cvt_pk_bf16_f32 v105, v100, v101
	v_cvt_pk_bf16_f32 v94, v94, v95
	v_cvt_pk_bf16_f32 v95, v96, v97
	v_cvt_pk_bf16_f32 v90, v90, v91
	v_cvt_pk_bf16_f32 v91, v92, v93
	v_cvt_pk_bf16_f32 v86, v86, v87
	v_cvt_pk_bf16_f32 v87, v88, v89
	v_cvt_pk_bf16_f32 v82, v82, v83
	v_cvt_pk_bf16_f32 v83, v84, v85
	v_cvt_pk_bf16_f32 v78, v78, v79
	v_cvt_pk_bf16_f32 v79, v80, v81
	v_cvt_pk_bf16_f32 v74, v74, v75
	v_cvt_pk_bf16_f32 v75, v76, v77
	v_cvt_pk_bf16_f32 v70, v70, v71
	v_cvt_pk_bf16_f32 v71, v72, v73
	v_cvt_pk_bf16_f32 v66, v66, v67
	v_cvt_pk_bf16_f32 v67, v68, v69
	v_cvt_pk_bf16_f32 v62, v62, v63
	v_cvt_pk_bf16_f32 v63, v64, v65
	v_cvt_pk_bf16_f32 v58, v58, v59
	v_cvt_pk_bf16_f32 v59, v60, v61
	v_cvt_pk_bf16_f32 v54, v54, v55
	v_cvt_pk_bf16_f32 v55, v56, v57
	v_cvt_pk_bf16_f32 v50, v50, v51
	v_cvt_pk_bf16_f32 v51, v52, v53
	v_cvt_pk_bf16_f32 v46, v46, v47
	v_cvt_pk_bf16_f32 v47, v48, v49
	v_cvt_pk_bf16_f32 v42, v42, v43
	v_cvt_pk_bf16_f32 v43, v44, v45
	v_cvt_pk_bf16_f32 v38, v38, v39
	v_cvt_pk_bf16_f32 v39, v40, v41
	v_cvt_pk_bf16_f32 v34, v34, v35
	v_cvt_pk_bf16_f32 v35, v36, v37
	v_cvt_pk_bf16_f32 v30, v30, v31
	v_cvt_pk_bf16_f32 v31, v32, v33
	v_cvt_pk_bf16_f32 v26, v26, v27
	v_cvt_pk_bf16_f32 v27, v28, v29
	v_cvt_pk_bf16_f32 v22, v22, v23
	v_cvt_pk_bf16_f32 v23, v24, v25
	v_cvt_pk_bf16_f32 v18, v18, v19
	v_cvt_pk_bf16_f32 v19, v20, v21
	v_cvt_pk_bf16_f32 v14, v14, v15
	v_cvt_pk_bf16_f32 v15, v16, v17
	v_cvt_pk_bf16_f32 v10, v10, v11
	v_cvt_pk_bf16_f32 v11, v12, v13
	v_cvt_pk_bf16_f32 v6, v6, v7
	v_cvt_pk_bf16_f32 v7, v8, v9
	v_cvt_pk_bf16_f32 v2, v2, v3
	v_cvt_pk_bf16_f32 v3, v4, v5
	s_and_b64 vcc, exec, s[0:1]
	s_mov_b32 s20, s27
	s_mov_b32 s30, s42
	s_mov_b32 s23, s29
	global_store_dwordx2 v[122:123], v[94:95], off offset:32
	global_store_dwordx2 v[124:125], v[90:91], off offset:32
	global_store_dwordx2 v[126:127], v[86:87], off offset:32
	global_store_dwordx2 v[128:129], v[82:83], off offset:32
	v_bfe_u32 v216, v225, 4, 1
	v_mov_b32_e32 v217, 0
	v_mul_u32_u24_e32 v216, 24, v216
	v_lshl_add_u64 v[194:195], v[122:123], 0, v[216:217]
	v_lshl_add_u64 v[196:197], v[124:125], 0, v[216:217]
	v_lshl_add_u64 v[198:199], v[126:127], 0, v[216:217]
	v_lshl_add_u64 v[200:201], v[128:129], 0, v[216:217]
	v_lshl_add_u64 v[202:203], v[110:111], 0, v[216:217]
	v_lshl_add_u64 v[204:205], v[106:107], 0, v[216:217]
	v_lshl_add_u64 v[206:207], v[102:103], 0, v[216:217]
	v_lshl_add_u64 v[208:209], v[98:99], 0, v[216:217]
	v_mov_b32_e32 v64, v30
	v_mov_b32_e32 v65, v31
	v_mov_b32_e32 v60, v26
	v_mov_b32_e32 v61, v27
	v_mov_b32_e32 v56, v22
	v_mov_b32_e32 v57, v23
	v_mov_b32_e32 v52, v18
	v_mov_b32_e32 v53, v19
	v_mov_b32_e32 v48, v14
	v_mov_b32_e32 v49, v15
	v_mov_b32_e32 v44, v10
	v_mov_b32_e32 v45, v11
	v_mov_b32_e32 v40, v6
	v_mov_b32_e32 v41, v7
	v_mov_b32_e32 v36, v2
	v_mov_b32_e32 v37, v3
	v_mov_b32_e32 v80, v78
	v_mov_b32_e32 v81, v79
	v_mov_b32_e32 v78, v130
	v_mov_b32_e32 v79, v131
	v_mov_b32_e32 v76, v74
	v_mov_b32_e32 v77, v75
	v_mov_b32_e32 v74, v112
	v_mov_b32_e32 v75, v113
	v_mov_b32_e32 v72, v70
	v_mov_b32_e32 v73, v71
	v_mov_b32_e32 v70, v108
	v_mov_b32_e32 v71, v109
	v_mov_b32_e32 v68, v66
	v_mov_b32_e32 v69, v67
	v_mov_b32_e32 v66, v104
	v_mov_b32_e32 v67, v105
	s_nop 1
	v_permlane16_swap_b32_e32 v62, v64
	v_permlane16_swap_b32_e32 v63, v65
	v_permlane16_swap_b32_e32 v58, v60
	v_permlane16_swap_b32_e32 v59, v61
	v_permlane16_swap_b32_e32 v54, v56
	v_permlane16_swap_b32_e32 v55, v57
	v_permlane16_swap_b32_e32 v50, v52
	v_permlane16_swap_b32_e32 v51, v53
	v_permlane16_swap_b32_e32 v46, v48
	v_permlane16_swap_b32_e32 v47, v49
	v_permlane16_swap_b32_e32 v42, v44
	v_permlane16_swap_b32_e32 v43, v45
	v_permlane16_swap_b32_e32 v38, v40
	v_permlane16_swap_b32_e32 v39, v41
	v_permlane16_swap_b32_e32 v34, v36
	v_permlane16_swap_b32_e32 v35, v37
	v_permlane16_swap_b32_e32 v78, v80
	v_permlane16_swap_b32_e32 v79, v81
	v_permlane16_swap_b32_e32 v74, v76
	v_permlane16_swap_b32_e32 v75, v77
	v_permlane16_swap_b32_e32 v70, v72
	v_permlane16_swap_b32_e32 v71, v73
	v_permlane16_swap_b32_e32 v66, v68
	v_permlane16_swap_b32_e32 v67, v69
	s_nop 1
	global_store_dwordx4 v[202:203], v[78:81], off
	global_store_dwordx4 v[204:205], v[74:77], off
	global_store_dwordx4 v[206:207], v[70:73], off
	global_store_dwordx4 v[208:209], v[66:69], off
	global_store_dwordx4 v[194:195], v[62:65], off offset:64
	global_store_dwordx4 v[196:197], v[58:61], off offset:64
	global_store_dwordx4 v[198:199], v[54:57], off offset:64
	global_store_dwordx4 v[200:201], v[50:53], off offset:64
	global_store_dwordx4 v[202:203], v[46:49], off offset:64
	global_store_dwordx4 v[204:205], v[42:45], off offset:64
	global_store_dwordx4 v[206:207], v[38:41], off offset:64
	global_store_dwordx4 v[208:209], v[34:37], off offset:64
	s_nop 1
	s_cbranch_vccnz .LBB0_223

; __global__ void __launch_bounds__(512, 2) fwd_mega(Params p, int ph_lo, int ph_hi, int coop) {
;   extern __shared__ __attribute__((aligned(16))) char lds[];
	.amdhsa_kernel _Z8fwd_mega6Paramsiii
		.amdhsa_group_segment_fixed_size 3104
		.amdhsa_private_segment_fixed_size 0
		.amdhsa_kernarg_size 480
		.amdhsa_user_sgpr_count 2
		.amdhsa_user_sgpr_dispatch_ptr 0
		.amdhsa_user_sgpr_queue_ptr 0
		.amdhsa_user_sgpr_kernarg_segment_ptr 1
		.amdhsa_user_sgpr_dispatch_id 0
		.amdhsa_user_sgpr_kernarg_preload_length 0
		.amdhsa_user_sgpr_kernarg_preload_offset 0
		.amdhsa_user_sgpr_private_segment_size 0
		.amdhsa_uses_dynamic_stack 0
		.amdhsa_enable_private_segment 0
		.amdhsa_system_sgpr_workgroup_id_x 1
		.amdhsa_system_sgpr_workgroup_id_y 0
		.amdhsa_system_sgpr_workgroup_id_z 0
		.amdhsa_system_sgpr_workgroup_info 0
		.amdhsa_system_vgpr_workitem_id 2
		.amdhsa_next_free_vgpr 256
		.amdhsa_next_free_sgpr 100
		.amdhsa_accum_offset 256
		.amdhsa_reserve_vcc 1
		.amdhsa_float_round_mode_32 0
		.amdhsa_float_round_mode_16_64 0
		.amdhsa_float_denorm_mode_32 3
		.amdhsa_float_denorm_mode_16_64 3
		.amdhsa_dx10_clamp 1
		.amdhsa_ieee_mode 1
		.amdhsa_fp16_overflow 0
		.amdhsa_tg_split 0
		.amdhsa_exception_fp_ieee_invalid_op 0
		.amdhsa_exception_fp_denorm_src 0
		.amdhsa_exception_fp_ieee_div_zero 0
		.amdhsa_exception_fp_ieee_overflow 0
		.amdhsa_exception_fp_ieee_underflow 0
		.amdhsa_exception_fp_ieee_inexact 0
		.amdhsa_exception_int_div_zero 0
	.end_amdhsa_kernel

; __global__ void __launch_bounds__(512, 2) fwd_mega(Params p, int ph_lo, int ph_hi, int coop) {
;   extern __shared__ __attribute__((aligned(16))) char lds[];
;   __shared__ uint4 xb_words;
;   __shared__ int nsa_cnt_s[4];
;   __shared__ float p4_stage[768];
amdhsa.kernels:
  - .agpr_count:     0
    .args:
      - .offset:         0
        .size:           208
        .value_kind:     by_value
      - .offset:         208
        .size:           4
        .value_kind:     by_value
      - .offset:         212
        .size:           4
        .value_kind:     by_value
      - .offset:         216
        .size:           4
        .value_kind:     by_value
      - .offset:         224
        .size:           4
        .value_kind:     hidden_block_count_x
      - .offset:         228
        .size:           4
        .value_kind:     hidden_block_count_y
      - .offset:         232
        .size:           4
        .value_kind:     hidden_block_count_z
      - .offset:         236
        .size:           2
        .value_kind:     hidden_group_size_x
      - .offset:         238
        .size:           2
        .value_kind:     hidden_group_size_y
      - .offset:         240
        .size:           2
        .value_kind:     hidden_group_size_z
      - .offset:         242
        .size:           2
        .value_kind:     hidden_remainder_x
      - .offset:         244
        .size:           2
        .value_kind:     hidden_remainder_y
      - .offset:         246
        .size:           2
        .value_kind:     hidden_remainder_z
      - .offset:         264
        .size:           8
        .value_kind:     hidden_global_offset_x
      - .offset:         272
        .size:           8
        .value_kind:     hidden_global_offset_y
      - .offset:         280
        .size:           8
        .value_kind:     hidden_global_offset_z
      - .offset:         288
        .size:           2
        .value_kind:     hidden_grid_dims
      - .offset:         312
        .size:           8
        .value_kind:     hidden_multigrid_sync_arg
      - .offset:         344
        .size:           4
        .value_kind:     hidden_dynamic_lds_size
    .group_segment_fixed_size: 3104
    .kernarg_segment_align: 8
    .kernarg_segment_size: 480
    .language:       OpenCL C
    .language_version:
      - 2
      - 0
    .max_flat_workgroup_size: 512
    .name:           _Z8fwd_mega6Paramsiii
    .private_segment_fixed_size: 0
    .sgpr_count:     106
    .sgpr_spill_count: 189
    .symbol:         _Z8fwd_mega6Paramsiii.kd
    .uniform_work_group_size: 1
    .uses_dynamic_stack: false
    .vgpr_count:     256
    .vgpr_spill_count: 0
    .wavefront_size: 64
